# publish checks in the barrier leaders: dropped the second L1 invalidate (nothing is loaded between the first invalidate and the check)
# speedup vs baseline: 1.0041x; 1.0008x over previous
; __device__ __forceinline__ void grid_bar(unsigned* ctr, unsigned target, bool leader) {
;     asm volatile("s_waitcnt vmcnt(0) lgkmcnt(0)" ::: "memory");
;     __syncthreads();
;     if (leader) {
;         __builtin_amdgcn_fence(__ATOMIC_RELEASE, "agent");
;         asm volatile("s_waitcnt vmcnt(0)" ::: "memory");
;         __hip_atomic_fetch_add(ctr, 1u, __ATOMIC_RELAXED, __HIP_MEMORY_SCOPE_AGENT);
;         while (__hip_atomic_load(ctr, __ATOMIC_RELAXED, __HIP_MEMORY_SCOPE_AGENT) < target) __builtin_amdgcn_s_sleep(2);
;         __builtin_amdgcn_fence(__ATOMIC_ACQUIRE, "agent");
;         asm volatile("s_waitcnt vmcnt(0)" ::: "memory");
;     }
;     __syncthreads();
; }
; __device__ __forceinline__ void xcd_local_bar(unsigned* ctr, unsigned target, bool leader) {
;     asm volatile("s_waitcnt vmcnt(0) lgkmcnt(0)" ::: "memory");
;     __syncthreads();
;     if (leader) {
;         __hip_atomic_fetch_add(ctr, 1u, __ATOMIC_RELAXED, __HIP_MEMORY_SCOPE_AGENT);
;         while (__hip_atomic_load(ctr, __ATOMIC_RELAXED, __HIP_MEMORY_SCOPE_AGENT) < target) __builtin_amdgcn_s_sleep(1);
;         __builtin_amdgcn_fence(__ATOMIC_ACQUIRE, "agent");
;         asm volatile("s_waitcnt vmcnt(0)" ::: "memory");
;     }
;     __syncthreads();
; }
.Lrd2_ok:
.LBB0_487:
	s_or_b64 exec, exec, s[8:9]
	s_barrier
	s_branch .LBB0_498

; __device__ __forceinline__ void grid_bar(unsigned* ctr, unsigned target, bool leader) {
;     asm volatile("s_waitcnt vmcnt(0) lgkmcnt(0)" ::: "memory");
;     __syncthreads();
;     if (leader) {
;         __builtin_amdgcn_fence(__ATOMIC_RELEASE, "agent");
;         asm volatile("s_waitcnt vmcnt(0)" ::: "memory");
;         __hip_atomic_fetch_add(ctr, 1u, __ATOMIC_RELAXED, __HIP_MEMORY_SCOPE_AGENT);
;         while (__hip_atomic_load(ctr, __ATOMIC_RELAXED, __HIP_MEMORY_SCOPE_AGENT) < target) __builtin_amdgcn_s_sleep(2);
;         __builtin_amdgcn_fence(__ATOMIC_ACQUIRE, "agent");
;         asm volatile("s_waitcnt vmcnt(0)" ::: "memory");
;     }
;     __syncthreads();
; }
; __device__ __forceinline__ void xcd_local_bar(unsigned* ctr, unsigned target, bool leader) {
;     asm volatile("s_waitcnt vmcnt(0) lgkmcnt(0)" ::: "memory");
;     __syncthreads();
;     if (leader) {
;         __hip_atomic_fetch_add(ctr, 1u, __ATOMIC_RELAXED, __HIP_MEMORY_SCOPE_AGENT);
;         while (__hip_atomic_load(ctr, __ATOMIC_RELAXED, __HIP_MEMORY_SCOPE_AGENT) < target) __builtin_amdgcn_s_sleep(1);
;         __builtin_amdgcn_fence(__ATOMIC_ACQUIRE, "agent");
;         asm volatile("s_waitcnt vmcnt(0)" ::: "memory");
;     }
;     __syncthreads();
; }
.Lrd3_ok:
.LBB0_589:
	s_or_b64 exec, exec, s[12:13]
	s_barrier
	s_branch .LBB0_600
